# v24 = v22 + PV phase exps rotated three MFMA gaps later
# baseline (speedup 1.0000x reference)
.Lstg_mid1:
	ds_read_b64_tr_b16 v[40:41], v167 offset:54272
	ds_read_b64_tr_b16 v[42:43], v167 offset:54784
	s_waitcnt lgkmcnt(6)
	v_mfma_f32_32x32x16_bf16 v[16:31], v[132:135], v[32:35], v[16:31]
	ds_read_b64_tr_b16 v[32:33], v167 offset:51200
	ds_read_b64_tr_b16 v[34:35], v167 offset:51712
	s_waitcnt lgkmcnt(6)
	v_mfma_f32_32x32x16_bf16 v[0:15], v[132:135], v[48:51], v[0:15]
	ds_read_b64_tr_b16 v[44:45], v167 offset:55296
	ds_read_b64_tr_b16 v[46:47], v167 offset:55808
	s_waitcnt lgkmcnt(6)
	v_mfma_f32_32x32x16_bf16 v[16:31], v[128:131], v[36:39], v[16:31]
	ds_read_b64_tr_b16 v[48:49], v167 offset:52224
	ds_read_b64_tr_b16 v[50:51], v167 offset:52736
	s_waitcnt lgkmcnt(6)
	v_mfma_f32_32x32x16_bf16 v[0:15], v[128:131], v[40:43], v[0:15]
	v_exp_f32_e32 v80, v80
	v_exp_f32_e32 v81, v81
	v_exp_f32_e32 v82, v82
	v_exp_f32_e32 v83, v83
	ds_read_b64_tr_b16 v[40:41], v167 offset:56320
	ds_read_b64_tr_b16 v[42:43], v167 offset:56832
	s_waitcnt lgkmcnt(6)
	v_mfma_f32_32x32x16_bf16 v[16:31], v[124:127], v[32:35], v[16:31]
	v_exp_f32_e32 v84, v84
	v_exp_f32_e32 v85, v85
	v_exp_f32_e32 v86, v86
	v_exp_f32_e32 v87, v87
	v_add_u32_e32 v142, s83, v179
	ds_read_b128 v[32:35], v142
	s_waitcnt lgkmcnt(5)
	v_mfma_f32_32x32x16_bf16 v[0:15], v[124:127], v[44:47], v[0:15]
	v_exp_f32_e32 v88, v88
	v_exp_f32_e32 v89, v89
	v_exp_f32_e32 v90, v90
	v_exp_f32_e32 v91, v91
	ds_read_b128 v[36:39], v142 offset:512
	s_waitcnt lgkmcnt(4)
	v_mfma_f32_32x32x16_bf16 v[16:31], v[120:123], v[48:51], v[16:31]
	v_exp_f32_e32 v92, v92
	v_exp_f32_e32 v93, v93
	v_exp_f32_e32 v94, v94
	v_exp_f32_e32 v95, v95
	ds_read_b128 v[136:139], v142 offset:2048
	s_waitcnt lgkmcnt(3)
	v_mfma_f32_32x32x16_bf16 v[0:15], v[120:123], v[40:43], v[0:15]
	v_exp_f32_e32 v64, v64
	v_exp_f32_e32 v65, v65
	v_exp_f32_e32 v66, v66
	v_exp_f32_e32 v67, v67
	v_exp_f32_e32 v68, v68
	v_exp_f32_e32 v69, v69
	v_exp_f32_e32 v70, v70
	v_exp_f32_e32 v71, v71
	v_exp_f32_e32 v72, v72
	v_exp_f32_e32 v73, v73
	v_exp_f32_e32 v74, v74
	v_exp_f32_e32 v75, v75
	v_exp_f32_e32 v76, v76
	v_exp_f32_e32 v77, v77
	v_exp_f32_e32 v78, v78
	v_exp_f32_e32 v79, v79
	s_cmp_lt_u32 s90, 4
	s_cbranch_scc0 .Lstg_end1
	s_waitcnt vmcnt(3) lgkmcnt(0)
	s_barrier

.Lstg_mid2:
	s_add_i32 s0, s83, 0x3000
	s_cmpk_lg_u32 s83, 0x9000
	s_cselect_b32 s82, s0, 0
	ds_read_b64_tr_b16 v[72:73], v141 offset:54272
	ds_read_b64_tr_b16 v[74:75], v141 offset:54784
	s_waitcnt lgkmcnt(6)
	v_mfma_f32_32x32x16_bf16 v[16:31], v[132:135], v[64:67], v[16:31]
	ds_read_b64_tr_b16 v[64:65], v141 offset:51200
	ds_read_b64_tr_b16 v[66:67], v141 offset:51712
	s_waitcnt lgkmcnt(6)
	v_mfma_f32_32x32x16_bf16 v[0:15], v[132:135], v[80:83], v[0:15]
	s_add_i32 s0, s79, 0x2000
	s_cmpk_lg_i32 s79, 0x4000
	s_cselect_b32 s0, s0, 0xe800
	s_cmpk_lg_u32 s79, 0xe800
	s_cselect_b32 s84, s0, 0
	ds_read_b64_tr_b16 v[76:77], v141 offset:55296
	ds_read_b64_tr_b16 v[78:79], v141 offset:55808
	s_waitcnt lgkmcnt(6)
	v_mfma_f32_32x32x16_bf16 v[16:31], v[128:131], v[68:71], v[16:31]
	s_add_i32 s0, s82, 0x3000
	s_cmpk_lg_u32 s82, 0x9000
	s_cselect_b32 s85, s0, 0
	ds_read_b64_tr_b16 v[68:69], v141 offset:52224
	ds_read_b64_tr_b16 v[70:71], v141 offset:52736
	s_waitcnt lgkmcnt(6)
	v_mfma_f32_32x32x16_bf16 v[0:15], v[128:131], v[72:75], v[0:15]
	v_exp_f32_e32 v48, v48
	v_exp_f32_e32 v49, v49
	v_exp_f32_e32 v50, v50
	v_exp_f32_e32 v51, v51
	s_add_u32 s68, s68, 0x30000
	s_addc_u32 s69, s69, 0
	ds_read_b64_tr_b16 v[72:73], v141 offset:56320
	ds_read_b64_tr_b16 v[74:75], v141 offset:56832
	s_waitcnt lgkmcnt(6)
	v_mfma_f32_32x32x16_bf16 v[16:31], v[124:127], v[64:67], v[16:31]
	v_exp_f32_e32 v52, v52
	v_exp_f32_e32 v53, v53
	v_exp_f32_e32 v54, v54
	v_exp_f32_e32 v55, v55
	s_add_u32 s48, s48, 0x48000
	s_addc_u32 s49, s49, 0
	v_add_u32_e32 v64, s82, v179
	ds_read_b128 v[80:83], v64
	s_waitcnt lgkmcnt(5)
	v_mfma_f32_32x32x16_bf16 v[0:15], v[124:127], v[76:79], v[0:15]
	v_exp_f32_e32 v56, v56
	v_exp_f32_e32 v57, v57
	v_exp_f32_e32 v58, v58
	v_exp_f32_e32 v59, v59
	s_add_u32 s8, s8, 0x2000
	s_addc_u32 s9, s9, 0
	ds_read_b128 v[136:139], v64 offset:512
	s_waitcnt lgkmcnt(4)
	v_mfma_f32_32x32x16_bf16 v[16:31], v[120:123], v[68:71], v[16:31]
	v_exp_f32_e32 v60, v60
	v_exp_f32_e32 v61, v61
	v_exp_f32_e32 v62, v62
	v_exp_f32_e32 v63, v63
	s_add_i32 s0, s87, 2
	ds_read_b128 v[140:143], v64 offset:2048
	s_waitcnt lgkmcnt(3)
	v_mfma_f32_32x32x16_bf16 v[0:15], v[120:123], v[72:75], v[0:15]
	v_exp_f32_e32 v32, v32
	v_exp_f32_e32 v33, v33
	v_exp_f32_e32 v34, v34
	v_exp_f32_e32 v35, v35
	v_exp_f32_e32 v36, v36
	v_exp_f32_e32 v37, v37
	v_exp_f32_e32 v38, v38
	v_exp_f32_e32 v39, v39
	v_exp_f32_e32 v40, v40
	v_exp_f32_e32 v41, v41
	v_exp_f32_e32 v42, v42
	v_exp_f32_e32 v43, v43
	v_exp_f32_e32 v44, v44
	v_exp_f32_e32 v45, v45
	v_exp_f32_e32 v46, v46
	v_exp_f32_e32 v47, v47
	s_cmp_lt_u32 s90, 4
	s_cbranch_scc0 .Lstg_end2
	s_waitcnt vmcnt(3) lgkmcnt(0)
	s_barrier
